# RG-LRU carry recurrences: all coefficient loads issued up-front instead of one dependent round trip per chunk
# speedup vs baseline: 1.1841x; 1.0033x over previous
.LBB0_149:
	s_waitcnt lgkmcnt(0)
	s_add_u32 s20, s6, 0xdeba000
	s_addc_u32 s21, s7, 0
	s_add_u32 s22, s6, 0xc5f6000
	s_addc_u32 s23, s7, 0
	s_add_u32 s10, s6, 0xddf6000
	s_addc_u32 s11, s7, 0
	s_add_u32 s12, s6, 0xde56000
	s_addc_u32 s13, s7, 0
	s_add_u32 s14, s6, 0xb3f6000
	v_ashrrev_i32_e32 v2, 4, v2
	s_addc_u32 s15, s7, 0
	s_and_b32 s5, s25, 48
	v_and_b32_e32 v2, -8, v2
	s_lshl_b32 s4, s28, 6
	v_add_u32_e32 v2, s5, v2
	s_ashr_i32 s5, s4, 31
	v_ashrrev_i32_e32 v3, 31, v2
	v_lshl_add_u64 v[4:5], v[2:3], 0, s[4:5]
	v_lshlrev_b64 v[10:11], 9, v[4:5]
	v_or_b32_e32 v10, v10, v12
	v_lshlrev_b64 v[8:9], 2, v[10:11]
	s_waitcnt vmcnt(4)
	v_lshl_add_u64 v[30:31], s[20:21], 0, v[8:9]
	s_mov_b32 s31, 0xc00000
	v_add_co_u32_e32 v16, vcc, s31, v30
	s_mov_b32 s34, 0xc01000
	s_nop 0
	v_addc_co_u32_e32 v17, vcc, 0, v31, vcc
	v_add_co_u32_e32 v34, vcc, s34, v30
	v_lshl_add_u64 v[32:33], s[22:23], 0, v[8:9]
	s_nop 0
	v_addc_co_u32_e32 v35, vcc, 0, v31, vcc
	v_add_co_u32_e32 v18, vcc, s31, v32
	v_lshl_add_u64 v[14:15], v[10:11], 1, s[14:15]
	s_nop 0
	v_addc_co_u32_e32 v19, vcc, 0, v33, vcc
	v_or_b32_e32 v20, 0x200, v10
	v_mov_b32_e32 v21, v11
	global_load_dword v6, v[30:31], off nt
	global_load_dword v7, v[34:35], off offset:-4096 nt
	global_load_ushort v26, v[14:15], off nt
	v_add_co_u32_e32 v36, vcc, s34, v32
	v_lshlrev_b64 v[14:15], 2, v[20:21]
	s_nop 0
	v_addc_co_u32_e32 v37, vcc, 0, v33, vcc
	v_lshl_add_u64 v[22:23], s[20:21], 0, v[14:15]
	global_load_dword v8, v[32:33], off nt
	global_load_dword v9, v[36:37], off offset:-4096 nt
	global_load_dword v3, v[22:23], off nt
	v_lshl_add_u64 v[14:15], s[22:23], 0, v[14:15]
	v_or_b32_e32 v22, 0x400, v10
	v_mov_b32_e32 v23, v11
	global_load_dword v14, v[14:15], off nt
	s_nop 0
	global_load_dword v13, v[16:17], off offset:2048 nt
	global_load_dword v15, v[18:19], off offset:2048 nt
	v_lshl_add_u64 v[16:17], v[20:21], 1, s[14:15]
	v_lshlrev_b64 v[18:19], 2, v[22:23]
	global_load_ushort v25, v[16:17], off nt
	v_lshl_add_u64 v[16:17], s[20:21], 0, v[18:19]
	v_lshl_add_u64 v[18:19], s[22:23], 0, v[18:19]
	v_lshl_add_u64 v[22:23], v[22:23], 1, s[14:15]
	v_or_b32_e32 v38, 0x600, v10
	v_mov_b32_e32 v39, v11
	global_load_dword v16, v[16:17], off nt
	s_nop 0
	global_load_dword v19, v[18:19], off nt
	s_nop 0
	global_load_dword v17, v[34:35], off nt
	global_load_dword v20, v[36:37], off nt
	global_load_ushort v29, v[22:23], off nt
	v_lshlrev_b64 v[22:23], 2, v[38:39]
	v_lshl_add_u64 v[40:41], s[20:21], 0, v[22:23]
	v_lshl_add_u64 v[22:23], s[22:23], 0, v[22:23]
	global_load_dword v18, v[40:41], off nt
	s_nop 0
	global_load_dword v23, v[22:23], off nt
	s_nop 0
	global_load_dword v21, v[34:35], off offset:2048 nt
	global_load_dword v24, v[36:37], off offset:2048 nt
	v_lshl_add_u64 v[34:35], v[38:39], 1, s[14:15]
	global_load_ushort v37, v[34:35], off nt
	v_or_b32_e32 v34, 0x800, v10
	v_mov_b32_e32 v35, v11
	v_lshlrev_b64 v[38:39], 2, v[34:35]
	v_lshl_add_u64 v[40:41], s[20:21], 0, v[38:39]
	v_lshl_add_u64 v[38:39], s[22:23], 0, v[38:39]
	s_mov_b32 s31, 0xc02000
	global_load_dword v27, v[38:39], off nt
	v_add_co_u32_e32 v38, vcc, s31, v30
	s_mov_b32 s34, 0xc03000
	s_nop 0
	v_addc_co_u32_e32 v39, vcc, 0, v31, vcc
	v_add_co_u32_e32 v48, vcc, s34, v30
	global_load_dword v22, v[40:41], off nt
	s_nop 0
	v_addc_co_u32_e32 v49, vcc, 0, v31, vcc
	v_lshl_add_u64 v[30:31], v[34:35], 1, s[14:15]
	global_load_ushort v44, v[30:31], off nt
	v_add_co_u32_e32 v40, vcc, s31, v32
	v_or_b32_e32 v42, 0xa00, v10
	s_nop 0
	v_addc_co_u32_e32 v41, vcc, 0, v33, vcc
	v_mov_b32_e32 v43, v11
	v_add_co_u32_e32 v50, vcc, s34, v32
	v_lshlrev_b64 v[34:35], 2, v[42:43]
	s_nop 0
	v_addc_co_u32_e32 v51, vcc, 0, v33, vcc
	v_lshl_add_u64 v[30:31], s[20:21], 0, v[34:35]
	v_lshl_add_u64 v[34:35], s[22:23], 0, v[34:35]
	global_load_dword v28, v[48:49], off offset:-4096 nt
	global_load_dword v32, v[50:51], off offset:-4096 nt
	s_cmp_ge_i32 s29, s28
	global_load_dword v31, v[30:31], off nt
	s_nop 0
	global_load_dword v35, v[34:35], off nt
	s_nop 0
	global_load_dword v33, v[38:39], off offset:2048 nt
	global_load_dword v36, v[40:41], off offset:2048 nt
	v_lshl_add_u64 v[38:39], v[42:43], 1, s[14:15]
	v_or_b32_e32 v42, 0xc00, v10
	global_load_ushort v45, v[38:39], off nt
	v_lshlrev_b64 v[38:39], 2, v[42:43]
	v_lshl_add_u64 v[40:41], s[20:21], 0, v[38:39]
	v_lshl_add_u64 v[38:39], s[22:23], 0, v[38:39]
	v_lshl_add_u64 v[42:43], v[42:43], 1, s[14:15]
	v_or_b32_e32 v10, 0xe00, v10
	global_load_dword v34, v[40:41], off nt
	s_nop 0
	global_load_dword v39, v[38:39], off nt
	s_nop 0
	global_load_dword v38, v[48:49], off nt
	global_load_dword v40, v[50:51], off nt
	global_load_ushort v46, v[42:43], off nt
	v_lshlrev_b64 v[42:43], 2, v[10:11]
	v_lshl_add_u64 v[52:53], s[20:21], 0, v[42:43]
	v_lshl_add_u64 v[42:43], s[22:23], 0, v[42:43]
	global_load_dword v30, v[52:53], off nt
	s_nop 0
	global_load_dword v42, v[42:43], off nt
	s_nop 0
	global_load_dword v41, v[48:49], off offset:2048 nt
	global_load_dword v43, v[50:51], off offset:2048 nt
	v_lshl_add_u64 v[10:11], v[10:11], 1, s[14:15]
	global_load_ushort v47, v[10:11], off nt
	v_lshlrev_b32_e32 v10, 2, v12
	s_add_i32 s15, s29, s30
	s_add_i32 s15, s15, -1
	s_add_i32 s14, s29, 0
	s_cmp_lt_i32 s14, s28
	s_cbranch_scc0 .Llru2_fi
	s_lshl_b32 s14, s14, 11
	s_add_u32 s98, s10, s14
	s_addc_u32 s99, s11, 0
	s_add_u32 s100, s12, s14
	s_addc_u32 s101, s13, 0
	global_load_dword v56, v10, s[98:99]
	global_load_dword v57, v10, s[100:101]
	s_add_i32 s14, s29, 1
	s_cmp_lt_i32 s14, s28
	s_cbranch_scc0 .Llru2_fi
	s_lshl_b32 s14, s14, 11
	s_add_u32 s98, s10, s14
	s_addc_u32 s99, s11, 0
	s_add_u32 s100, s12, s14
	s_addc_u32 s101, s13, 0
	global_load_dword v58, v10, s[98:99]
	global_load_dword v59, v10, s[100:101]
	s_add_i32 s14, s29, 2
	s_cmp_lt_i32 s14, s28
	s_cbranch_scc0 .Llru2_fi
	s_lshl_b32 s14, s14, 11
	s_add_u32 s98, s10, s14
	s_addc_u32 s99, s11, 0
	s_add_u32 s100, s12, s14
	s_addc_u32 s101, s13, 0
	global_load_dword v60, v10, s[98:99]
	global_load_dword v61, v10, s[100:101]
	s_add_i32 s14, s29, 3
	s_cmp_lt_i32 s14, s28
	s_cbranch_scc0 .Llru2_fi
	s_lshl_b32 s14, s14, 11
	s_add_u32 s98, s10, s14
	s_addc_u32 s99, s11, 0
	s_add_u32 s100, s12, s14
	s_addc_u32 s101, s13, 0
	global_load_dword v62, v10, s[98:99]
	global_load_dword v63, v10, s[100:101]
	s_add_i32 s14, s29, 4
	s_cmp_lt_i32 s14, s28
	s_cbranch_scc0 .Llru2_fi
	s_lshl_b32 s14, s14, 11
	s_add_u32 s98, s10, s14
	s_addc_u32 s99, s11, 0
	s_add_u32 s100, s12, s14
	s_addc_u32 s101, s13, 0
	global_load_dword v64, v10, s[98:99]
	global_load_dword v65, v10, s[100:101]
	s_add_i32 s14, s29, 5
	s_cmp_lt_i32 s14, s28
	s_cbranch_scc0 .Llru2_fi
	s_lshl_b32 s14, s14, 11
	s_add_u32 s98, s10, s14
	s_addc_u32 s99, s11, 0
	s_add_u32 s100, s12, s14
	s_addc_u32 s101, s13, 0
	global_load_dword v66, v10, s[98:99]
	global_load_dword v67, v10, s[100:101]
	s_add_i32 s14, s29, 6
	s_cmp_lt_i32 s14, s28
	s_cbranch_scc0 .Llru2_fi
	s_lshl_b32 s14, s14, 11
	s_add_u32 s98, s10, s14
	s_addc_u32 s99, s11, 0
	s_add_u32 s100, s12, s14
	s_addc_u32 s101, s13, 0
	global_load_dword v68, v10, s[98:99]
	global_load_dword v69, v10, s[100:101]
	s_add_i32 s14, s29, 7
	s_cmp_lt_i32 s14, s28
	s_cbranch_scc0 .Llru2_fi
	s_lshl_b32 s14, s14, 11
	s_add_u32 s98, s10, s14
	s_addc_u32 s99, s11, 0
	s_add_u32 s100, s12, s14
	s_addc_u32 s101, s13, 0
	global_load_dword v70, v10, s[98:99]
	global_load_dword v71, v10, s[100:101]
	s_add_i32 s14, s29, 8
	s_cmp_lt_i32 s14, s28
	s_cbranch_scc0 .Llru2_fi
	s_lshl_b32 s14, s14, 11
	s_add_u32 s98, s10, s14
	s_addc_u32 s99, s11, 0
	s_add_u32 s100, s12, s14
	s_addc_u32 s101, s13, 0
	global_load_dword v72, v10, s[98:99]
	global_load_dword v73, v10, s[100:101]
	s_add_i32 s14, s29, 9
	s_cmp_lt_i32 s14, s28
	s_cbranch_scc0 .Llru2_fi
	s_lshl_b32 s14, s14, 11
	s_add_u32 s98, s10, s14
	s_addc_u32 s99, s11, 0
	s_add_u32 s100, s12, s14
	s_addc_u32 s101, s13, 0
	global_load_dword v74, v10, s[98:99]
	global_load_dword v75, v10, s[100:101]
	s_add_i32 s14, s29, 10
	s_cmp_lt_i32 s14, s28
	s_cbranch_scc0 .Llru2_fi
	s_lshl_b32 s14, s14, 11
	s_add_u32 s98, s10, s14
	s_addc_u32 s99, s11, 0
	s_add_u32 s100, s12, s14
	s_addc_u32 s101, s13, 0
	global_load_dword v76, v10, s[98:99]
	global_load_dword v77, v10, s[100:101]
	s_add_i32 s14, s29, 11
	s_cmp_lt_i32 s14, s28
	s_cbranch_scc0 .Llru2_fi
	s_lshl_b32 s14, s14, 11
	s_add_u32 s98, s10, s14
	s_addc_u32 s99, s11, 0
	s_add_u32 s100, s12, s14
	s_addc_u32 s101, s13, 0
	global_load_dword v78, v10, s[98:99]
	global_load_dword v79, v10, s[100:101]
	s_add_i32 s14, s29, 12
	s_cmp_lt_i32 s14, s28
	s_cbranch_scc0 .Llru2_fi
	s_lshl_b32 s14, s14, 11
	s_add_u32 s98, s10, s14
	s_addc_u32 s99, s11, 0
	s_add_u32 s100, s12, s14
	s_addc_u32 s101, s13, 0
	global_load_dword v80, v10, s[98:99]
	global_load_dword v81, v10, s[100:101]
	s_add_i32 s14, s29, 13
	s_cmp_lt_i32 s14, s28
	s_cbranch_scc0 .Llru2_fi
	s_lshl_b32 s14, s14, 11
	s_add_u32 s98, s10, s14
	s_addc_u32 s99, s11, 0
	s_add_u32 s100, s12, s14
	s_addc_u32 s101, s13, 0
	global_load_dword v83, v10, s[98:99]
	global_load_dword v84, v10, s[100:101]
	s_add_i32 s14, s29, 14
	s_cmp_lt_i32 s14, s28
	s_cbranch_scc0 .Llru2_fi
	s_lshl_b32 s14, s14, 11
	s_add_u32 s98, s10, s14
	s_addc_u32 s99, s11, 0
	s_add_u32 s100, s12, s14
	s_addc_u32 s101, s13, 0
	global_load_dword v85, v10, s[98:99]
	global_load_dword v86, v10, s[100:101]
	s_add_i32 s14, s29, 15
	s_cmp_lt_i32 s14, s28
	s_cbranch_scc0 .Llru2_fi
	s_lshl_b32 s14, s14, 11
	s_add_u32 s98, s10, s14
	s_addc_u32 s99, s11, 0
	s_add_u32 s100, s12, s14
	s_addc_u32 s101, s13, 0
	global_load_dword v87, v10, s[98:99]
	global_load_dword v88, v10, s[100:101]
.Llru2_fi:
	s_sub_i32 s14, s15, 0
	s_cmp_gt_i32 s14, s28
	s_cbranch_scc0 .Llru2_bi
	s_add_i32 s14, s14, 0x60
	s_lshl_b32 s14, s14, 11
	s_add_u32 s98, s10, s14
	s_addc_u32 s99, s11, 0
	s_add_u32 s100, s12, s14
	s_addc_u32 s101, s13, 0
	global_load_dword v89, v10, s[98:99]
	global_load_dword v90, v10, s[100:101]
	s_sub_i32 s14, s15, 1
	s_cmp_gt_i32 s14, s28
	s_cbranch_scc0 .Llru2_bi
	s_add_i32 s14, s14, 0x60
	s_lshl_b32 s14, s14, 11
	s_add_u32 s98, s10, s14
	s_addc_u32 s99, s11, 0
	s_add_u32 s100, s12, s14
	s_addc_u32 s101, s13, 0
	global_load_dword v91, v10, s[98:99]
	global_load_dword v92, v10, s[100:101]
	s_sub_i32 s14, s15, 2
	s_cmp_gt_i32 s14, s28
	s_cbranch_scc0 .Llru2_bi
	s_add_i32 s14, s14, 0x60
	s_lshl_b32 s14, s14, 11
	s_add_u32 s98, s10, s14
	s_addc_u32 s99, s11, 0
	s_add_u32 s100, s12, s14
	s_addc_u32 s101, s13, 0
	global_load_dword v93, v10, s[98:99]
	global_load_dword v94, v10, s[100:101]
	s_sub_i32 s14, s15, 3
	s_cmp_gt_i32 s14, s28
	s_cbranch_scc0 .Llru2_bi
	s_add_i32 s14, s14, 0x60
	s_lshl_b32 s14, s14, 11
	s_add_u32 s98, s10, s14
	s_addc_u32 s99, s11, 0
	s_add_u32 s100, s12, s14
	s_addc_u32 s101, s13, 0
	global_load_dword v95, v10, s[98:99]
	global_load_dword v96, v10, s[100:101]
	s_sub_i32 s14, s15, 4
	s_cmp_gt_i32 s14, s28
	s_cbranch_scc0 .Llru2_bi
	s_add_i32 s14, s14, 0x60
	s_lshl_b32 s14, s14, 11
	s_add_u32 s98, s10, s14
	s_addc_u32 s99, s11, 0
	s_add_u32 s100, s12, s14
	s_addc_u32 s101, s13, 0
	global_load_dword v97, v10, s[98:99]
	global_load_dword v98, v10, s[100:101]
	s_sub_i32 s14, s15, 5
	s_cmp_gt_i32 s14, s28
	s_cbranch_scc0 .Llru2_bi
	s_add_i32 s14, s14, 0x60
	s_lshl_b32 s14, s14, 11
	s_add_u32 s98, s10, s14
	s_addc_u32 s99, s11, 0
	s_add_u32 s100, s12, s14
	s_addc_u32 s101, s13, 0
	global_load_dword v99, v10, s[98:99]
	global_load_dword v100, v10, s[100:101]
	s_sub_i32 s14, s15, 6
	s_cmp_gt_i32 s14, s28
	s_cbranch_scc0 .Llru2_bi
	s_add_i32 s14, s14, 0x60
	s_lshl_b32 s14, s14, 11
	s_add_u32 s98, s10, s14
	s_addc_u32 s99, s11, 0
	s_add_u32 s100, s12, s14
	s_addc_u32 s101, s13, 0
	global_load_dword v101, v10, s[98:99]
	global_load_dword v102, v10, s[100:101]
	s_sub_i32 s14, s15, 7
	s_cmp_gt_i32 s14, s28
	s_cbranch_scc0 .Llru2_bi
	s_add_i32 s14, s14, 0x60
	s_lshl_b32 s14, s14, 11
	s_add_u32 s98, s10, s14
	s_addc_u32 s99, s11, 0
	s_add_u32 s100, s12, s14
	s_addc_u32 s101, s13, 0
	global_load_dword v103, v10, s[98:99]
	global_load_dword v104, v10, s[100:101]
	s_sub_i32 s14, s15, 8
	s_cmp_gt_i32 s14, s28
	s_cbranch_scc0 .Llru2_bi
	s_add_i32 s14, s14, 0x60
	s_lshl_b32 s14, s14, 11
	s_add_u32 s98, s10, s14
	s_addc_u32 s99, s11, 0
	s_add_u32 s100, s12, s14
	s_addc_u32 s101, s13, 0
	global_load_dword v105, v10, s[98:99]
	global_load_dword v106, v10, s[100:101]
	s_sub_i32 s14, s15, 9
	s_cmp_gt_i32 s14, s28
	s_cbranch_scc0 .Llru2_bi
	s_add_i32 s14, s14, 0x60
	s_lshl_b32 s14, s14, 11
	s_add_u32 s98, s10, s14
	s_addc_u32 s99, s11, 0
	s_add_u32 s100, s12, s14
	s_addc_u32 s101, s13, 0
	global_load_dword v107, v10, s[98:99]
	global_load_dword v108, v10, s[100:101]
	s_sub_i32 s14, s15, 10
	s_cmp_gt_i32 s14, s28
	s_cbranch_scc0 .Llru2_bi
	s_add_i32 s14, s14, 0x60
	s_lshl_b32 s14, s14, 11
	s_add_u32 s98, s10, s14
	s_addc_u32 s99, s11, 0
	s_add_u32 s100, s12, s14
	s_addc_u32 s101, s13, 0
	global_load_dword v109, v10, s[98:99]
	global_load_dword v110, v10, s[100:101]
	s_sub_i32 s14, s15, 11
	s_cmp_gt_i32 s14, s28
	s_cbranch_scc0 .Llru2_bi
	s_add_i32 s14, s14, 0x60
	s_lshl_b32 s14, s14, 11
	s_add_u32 s98, s10, s14
	s_addc_u32 s99, s11, 0
	s_add_u32 s100, s12, s14
	s_addc_u32 s101, s13, 0
	global_load_dword v111, v10, s[98:99]
	global_load_dword v112, v10, s[100:101]
	s_sub_i32 s14, s15, 12
	s_cmp_gt_i32 s14, s28
	s_cbranch_scc0 .Llru2_bi
	s_add_i32 s14, s14, 0x60
	s_lshl_b32 s14, s14, 11
	s_add_u32 s98, s10, s14
	s_addc_u32 s99, s11, 0
	s_add_u32 s100, s12, s14
	s_addc_u32 s101, s13, 0
	global_load_dword v113, v10, s[98:99]
	global_load_dword v114, v10, s[100:101]
	s_sub_i32 s14, s15, 13
	s_cmp_gt_i32 s14, s28
	s_cbranch_scc0 .Llru2_bi
	s_add_i32 s14, s14, 0x60
	s_lshl_b32 s14, s14, 11
	s_add_u32 s98, s10, s14
	s_addc_u32 s99, s11, 0
	s_add_u32 s100, s12, s14
	s_addc_u32 s101, s13, 0
	global_load_dword v115, v10, s[98:99]
	global_load_dword v116, v10, s[100:101]
	s_sub_i32 s14, s15, 14
	s_cmp_gt_i32 s14, s28
	s_cbranch_scc0 .Llru2_bi
	s_add_i32 s14, s14, 0x60
	s_lshl_b32 s14, s14, 11
	s_add_u32 s98, s10, s14
	s_addc_u32 s99, s11, 0
	s_add_u32 s100, s12, s14
	s_addc_u32 s101, s13, 0
	global_load_dword v117, v10, s[98:99]
	global_load_dword v118, v10, s[100:101]
	s_sub_i32 s14, s15, 15
	s_cmp_gt_i32 s14, s28
	s_cbranch_scc0 .Llru2_bi
	s_add_i32 s14, s14, 0x60
	s_lshl_b32 s14, s14, 11
	s_add_u32 s98, s10, s14
	s_addc_u32 s99, s11, 0
	s_add_u32 s100, s12, s14
	s_addc_u32 s101, s13, 0
	global_load_dword v119, v10, s[98:99]
	global_load_dword v120, v10, s[100:101]
.Llru2_bi:
	s_waitcnt vmcnt(0)
	s_add_i32 s14, s29, 0
	s_cmp_lt_i32 s14, s28
	s_cbranch_scc0 .Llru2_fc
	v_fma_f32 v0, v56, v0, v57
	s_add_i32 s14, s29, 1
	s_cmp_lt_i32 s14, s28
	s_cbranch_scc0 .Llru2_fc
	v_fma_f32 v0, v58, v0, v59
	s_add_i32 s14, s29, 2
	s_cmp_lt_i32 s14, s28
	s_cbranch_scc0 .Llru2_fc
	v_fma_f32 v0, v60, v0, v61
	s_add_i32 s14, s29, 3
	s_cmp_lt_i32 s14, s28
	s_cbranch_scc0 .Llru2_fc
	v_fma_f32 v0, v62, v0, v63
	s_add_i32 s14, s29, 4
	s_cmp_lt_i32 s14, s28
	s_cbranch_scc0 .Llru2_fc
	v_fma_f32 v0, v64, v0, v65
	s_add_i32 s14, s29, 5
	s_cmp_lt_i32 s14, s28
	s_cbranch_scc0 .Llru2_fc
	v_fma_f32 v0, v66, v0, v67
	s_add_i32 s14, s29, 6
	s_cmp_lt_i32 s14, s28
	s_cbranch_scc0 .Llru2_fc
	v_fma_f32 v0, v68, v0, v69
	s_add_i32 s14, s29, 7
	s_cmp_lt_i32 s14, s28
	s_cbranch_scc0 .Llru2_fc
	v_fma_f32 v0, v70, v0, v71
	s_add_i32 s14, s29, 8
	s_cmp_lt_i32 s14, s28
	s_cbranch_scc0 .Llru2_fc
	v_fma_f32 v0, v72, v0, v73
	s_add_i32 s14, s29, 9
	s_cmp_lt_i32 s14, s28
	s_cbranch_scc0 .Llru2_fc
	v_fma_f32 v0, v74, v0, v75
	s_add_i32 s14, s29, 10
	s_cmp_lt_i32 s14, s28
	s_cbranch_scc0 .Llru2_fc
	v_fma_f32 v0, v76, v0, v77
	s_add_i32 s14, s29, 11
	s_cmp_lt_i32 s14, s28
	s_cbranch_scc0 .Llru2_fc
	v_fma_f32 v0, v78, v0, v79
	s_add_i32 s14, s29, 12
	s_cmp_lt_i32 s14, s28
	s_cbranch_scc0 .Llru2_fc
	v_fma_f32 v0, v80, v0, v81
	s_add_i32 s14, s29, 13
	s_cmp_lt_i32 s14, s28
	s_cbranch_scc0 .Llru2_fc
	v_fma_f32 v0, v83, v0, v84
	s_add_i32 s14, s29, 14
	s_cmp_lt_i32 s14, s28
	s_cbranch_scc0 .Llru2_fc
	v_fma_f32 v0, v85, v0, v86
	s_add_i32 s14, s29, 15
	s_cmp_lt_i32 s14, s28
	s_cbranch_scc0 .Llru2_fc
	v_fma_f32 v0, v87, v0, v88
.Llru2_fc:
	s_sub_i32 s14, s15, 0
	s_cmp_gt_i32 s14, s28
	s_cbranch_scc0 .Llru2_bc
	v_fma_f32 v1, v89, v1, v90
	s_sub_i32 s14, s15, 1
	s_cmp_gt_i32 s14, s28
	s_cbranch_scc0 .Llru2_bc
	v_fma_f32 v1, v91, v1, v92
	s_sub_i32 s14, s15, 2
	s_cmp_gt_i32 s14, s28
	s_cbranch_scc0 .Llru2_bc
	v_fma_f32 v1, v93, v1, v94
	s_sub_i32 s14, s15, 3
	s_cmp_gt_i32 s14, s28
	s_cbranch_scc0 .Llru2_bc
	v_fma_f32 v1, v95, v1, v96
	s_sub_i32 s14, s15, 4
	s_cmp_gt_i32 s14, s28
	s_cbranch_scc0 .Llru2_bc
	v_fma_f32 v1, v97, v1, v98
	s_sub_i32 s14, s15, 5
	s_cmp_gt_i32 s14, s28
	s_cbranch_scc0 .Llru2_bc
	v_fma_f32 v1, v99, v1, v100
	s_sub_i32 s14, s15, 6
	s_cmp_gt_i32 s14, s28
	s_cbranch_scc0 .Llru2_bc
	v_fma_f32 v1, v101, v1, v102
	s_sub_i32 s14, s15, 7
	s_cmp_gt_i32 s14, s28
	s_cbranch_scc0 .Llru2_bc
	v_fma_f32 v1, v103, v1, v104
	s_sub_i32 s14, s15, 8
	s_cmp_gt_i32 s14, s28
	s_cbranch_scc0 .Llru2_bc
	v_fma_f32 v1, v105, v1, v106
	s_sub_i32 s14, s15, 9
	s_cmp_gt_i32 s14, s28
	s_cbranch_scc0 .Llru2_bc
	v_fma_f32 v1, v107, v1, v108
	s_sub_i32 s14, s15, 10
	s_cmp_gt_i32 s14, s28
	s_cbranch_scc0 .Llru2_bc
	v_fma_f32 v1, v109, v1, v110
	s_sub_i32 s14, s15, 11
	s_cmp_gt_i32 s14, s28
	s_cbranch_scc0 .Llru2_bc
	v_fma_f32 v1, v111, v1, v112
	s_sub_i32 s14, s15, 12
	s_cmp_gt_i32 s14, s28
	s_cbranch_scc0 .Llru2_bc
	v_fma_f32 v1, v113, v1, v114
	s_sub_i32 s14, s15, 13
	s_cmp_gt_i32 s14, s28
	s_cbranch_scc0 .Llru2_bc
	v_fma_f32 v1, v115, v1, v116
	s_sub_i32 s14, s15, 14
	s_cmp_gt_i32 s14, s28
	s_cbranch_scc0 .Llru2_bc
	v_fma_f32 v1, v117, v1, v118
	s_sub_i32 s14, s15, 15
	s_cmp_gt_i32 s14, s28
	s_cbranch_scc0 .Llru2_bc
	v_fma_f32 v1, v119, v1, v120
.Llru2_bc:
.LBB0_213:
	s_waitcnt vmcnt(35)
	v_pk_fma_f32 v[6:7], v[8:9], v[0:1], v[6:7]
	v_lshlrev_b32_e32 v26, 16, v26
	v_lshlrev_b32_e32 v124, 1, v12
	v_add_f32_e32 v6, v6, v7
	v_lshl_add_u64 v[10:11], s[6:7], 0, v[124:125]
	s_mov_b64 s[6:7], 0xb9f6400
	v_mul_f32_e32 v6, v6, v26
	v_lshl_add_u64 v[10:11], v[10:11], 0, s[6:7]
	s_load_dwordx2 s[6:7], s[72:73], 0xf0
	v_bfe_u32 v8, v6, 16, 1
	v_lshlrev_b64 v[4:5], 11, v[4:5]
	s_and_b32 s13, s27, 48
	v_add3_u32 v6, v6, v8, s33
	v_lshl_add_u64 v[4:5], v[10:11], 0, v[4:5]
	global_store_short_d16_hi v[4:5], v6, off
	v_or_b32_e32 v4, s13, v2
	v_cmp_eq_u32_e32 vcc, 0, v4
	s_and_b32 s12, s26, 0xfffffe00
	s_and_b64 s[14:15], s[0:1], vcc
	s_and_saveexec_b64 s[10:11], s[14:15]
	s_cbranch_execz .LBB0_215
	s_add_i32 s14, s12, 0xa02000
	v_or_b32_e32 v4, s14, v12
	v_ashrrev_i32_e32 v5, 31, v4
	s_waitcnt lgkmcnt(0)
	v_lshl_add_u64 v[4:5], v[4:5], 2, s[6:7]
	global_store_dword v[4:5], v7, off
